# scan chunk loop: output store block of the MFMA waves issues its 8 LDS reads together (counted lgkmcnt) instead of 4 serial read/wait/store rounds
# speedup vs baseline: 1.0012x; 1.0012x over previous
.LBB0_402:
	s_cmp_eq_u32 s3, 0
	s_cselect_b64 s[20:21], -1, 0
	s_xor_b64 vcc, s[14:15], -1
	s_or_b64 s[20:21], vcc, s[20:21]
	s_and_b64 vcc, exec, s[20:21]
	s_cbranch_vccnz .LBB0_404
	v_add_u32_e32 v80, s3, v134
	v_cmp_lt_i32_e32 vcc, s33, v80
	v_add_u32_e32 v86, s7, v129
	ds_read2st64_b32 v[82:83], v86 offset1:1
	ds_read2st64_b32 v[84:85], v86 offset0:2 offset1:3
	ds_read2st64_b32 v[88:89], v86 offset0:4 offset1:5
	ds_read2st64_b32 v[90:91], v86 offset0:6 offset1:7
	ds_read2st64_b32 v[92:93], v86 offset0:8 offset1:9
	ds_read2st64_b32 v[94:95], v86 offset0:10 offset1:11
	ds_read2st64_b32 v[96:97], v86 offset0:12 offset1:13
	ds_read2st64_b32 v[98:99], v86 offset0:14 offset1:15
	v_cndmask_b32_e32 v81, v207, v208, vcc
	v_add_u32_e32 v81, v81, v180
	v_cndmask_b32_e64 v80, v81, v80, s[76:77]
	v_ashrrev_i32_e32 v81, 31, v80
	v_lshl_add_u64 v[80:81], s[82:83], 0, v[80:81]
	v_lshlrev_b64 v[80:81], 12, v[80:81]
	s_waitcnt lgkmcnt(6)
	v_pk_add_f32 v[82:83], v[64:65], v[82:83]
	v_pk_add_f32 v[84:85], v[66:67], v[84:85]
	v_lshl_add_u64 v[80:81], v[126:127], 0, v[80:81]
	v_cvt_pk_bf16_f32 v82, v82, v83
	v_cvt_pk_bf16_f32 v83, v84, v85
	global_store_dwordx2 v[80:81], v[82:83], off
	s_waitcnt lgkmcnt(4)
	v_pk_add_f32 v[88:89], v[68:69], v[88:89]
	v_pk_add_f32 v[90:91], v[70:71], v[90:91]
	s_waitcnt lgkmcnt(2)
	v_pk_add_f32 v[92:93], v[72:73], v[92:93]
	v_pk_add_f32 v[94:95], v[74:75], v[94:95]
	v_cvt_pk_bf16_f32 v88, v88, v89
	v_cvt_pk_bf16_f32 v89, v90, v91
	global_store_dwordx2 v[80:81], v[88:89], off offset:16
	s_waitcnt lgkmcnt(0)
	v_pk_add_f32 v[96:97], v[76:77], v[96:97]
	v_pk_add_f32 v[98:99], v[78:79], v[98:99]
	v_cvt_pk_bf16_f32 v92, v92, v93
	v_cvt_pk_bf16_f32 v93, v94, v95
	global_store_dwordx2 v[80:81], v[92:93], off offset:32
	v_cvt_pk_bf16_f32 v96, v96, v97
	v_cvt_pk_bf16_f32 v97, v98, v99
	global_store_dwordx2 v[80:81], v[96:97], off offset:48
